# ln_router L1: next-token row prefetch issued after the parameter rounds so their waits do not cover the HBM prefetch
# baseline (speedup 1.0000x reference)
.LBB0_1868:
	s_waitcnt vmcnt(0)
	s_or_b64 exec, exec, s[2:3]
	s_and_b64 s[2:3], exec, s[14:15]
	s_or_b64 s[22:23], s[2:3], s[22:23]
	v_mov_b32_e32 v32, v68
	v_mov_b64_e32 v[28:29], v[0:1]
	v_mov_b64_e32 v[30:31], v[2:3]
	v_mov_b64_e32 v[24:25], v[4:5]
	v_mov_b64_e32 v[26:27], v[6:7]
	v_mov_b64_e32 v[20:21], v[8:9]
	v_mov_b64_e32 v[22:23], v[10:11]
	v_mov_b64_e32 v[16:17], v[12:13]
	v_mov_b64_e32 v[18:19], v[14:15]
	s_andn2_b64 exec, exec, s[22:23]
	s_cbranch_execz .LBB0_1875
.LBB0_1869:
	v_add_u32_e32 v68, s30, v32
	v_cmp_lt_i32_e32 vcc, s10, v32
	v_cmp_gt_i32_e64 s[18:19], s25, v68
	v_cmp_lt_i32_e64 s[14:15], s11, v68
	v_add_u32_e32 v33, 0xfffff000, v32
	v_lshrrev_b32_e32 v33, 11, v33
	v_add_u32_e32 v33, 4, v33
	v_cndmask_b32_e32 v33, 3, v33, vcc
	v_mad_u64_u32 v[74:75], s[2:3], v33, s31, v[60:61]
	v_lshl_add_u64 v[90:91], v[74:75], 0, s[26:27]
	v_lshl_add_u64 v[92:93], v[74:75], 0, s[28:29]
	v_lshl_add_u64 v[82:83], v[90:91], 0, v[34:35]
	v_lshl_add_u64 v[86:87], v[92:93], 0, v[34:35]
	global_load_dwordx4 v[74:77], v[38:39], off
	global_load_dwordx4 v[78:81], v[40:41], off
	s_nop 0
	global_load_dwordx4 v[82:85], v[82:83], off
	s_nop 0
	global_load_dwordx4 v[86:89], v[86:87], off
	v_add_f32_e32 v69, v28, v29
	v_add_f32_e32 v33, v69, v30
	v_add_f32_e32 v69, v24, v25
	v_add_f32_e32 v33, v33, v31
	v_add_f32_e32 v69, v69, v26
	v_add_f32_e32 v33, 0, v33
	v_add_f32_e32 v69, v69, v27
	v_add_f32_e32 v33, v33, v69
	v_add_f32_e32 v69, v20, v21
	v_add_f32_e32 v69, v69, v22
	v_add_f32_e32 v69, v69, v23
	v_add_f32_e32 v33, v33, v69
	v_add_f32_e32 v69, v16, v17
	v_add_f32_e32 v69, v69, v18
	v_add_f32_e32 v69, v69, v19
	v_pk_mul_f32 v[94:95], v[28:29], v[28:29]
	v_pk_mul_f32 v[98:99], v[24:25], v[24:25]
	v_add_f32_e32 v33, v33, v69
	v_pk_mul_f32 v[96:97], v[30:31], v[30:31]
	v_pk_mul_f32 v[100:101], v[26:27], v[26:27]
	v_add_f32_e32 v69, v98, v99
	v_add_f32_e32 v94, v94, v95
	v_add_f32_e32 v69, v69, v100
	v_add_f32_e32 v94, v94, v96
	v_pk_mul_f32 v[102:103], v[20:21], v[20:21]
	v_add_f32_e32 v69, v69, v101
	v_add_f32_e32 v94, v94, v97
	v_pk_mul_f32 v[104:105], v[22:23], v[22:23]
	v_add_f32_e32 v69, v94, v69
	v_add_f32_e32 v94, v102, v103
	v_add_f32_e32 v94, v94, v104
	v_pk_mul_f32 v[106:107], v[16:17], v[16:17]
	v_add_f32_e32 v94, v94, v105
	v_pk_mul_f32 v[108:109], v[18:19], v[18:19]
	v_add_f32_e32 v69, v69, v94
	v_add_f32_e32 v94, v106, v107
	v_add_f32_e32 v94, v94, v108
	v_add_f32_e32 v94, v94, v109
	v_add_f32_dpp v33, v33, v33 row_ror:8 row_mask:0xf bank_mask:0xf bound_ctrl:1
	v_add_f32_e32 v69, v69, v94
	s_nop 0
	v_add_f32_dpp v33, v33, v33 row_ror:4 row_mask:0xf bank_mask:0xf bound_ctrl:1
	v_add_f32_dpp v69, v69, v69 row_ror:8 row_mask:0xf bank_mask:0xf bound_ctrl:1
	s_nop 0
	v_add_f32_dpp v33, v33, v33 row_ror:2 row_mask:0xf bank_mask:0xf bound_ctrl:1
	v_add_f32_dpp v69, v69, v69 row_ror:4 row_mask:0xf bank_mask:0xf bound_ctrl:1
	s_nop 0
	v_add_f32_dpp v33, v33, v33 row_ror:1 row_mask:0xf bank_mask:0xf bound_ctrl:1
	v_add_f32_dpp v69, v69, v69 row_ror:2 row_mask:0xf bank_mask:0xf bound_ctrl:1
	v_mov_b32_e32 v94, v33
	s_nop 1
	v_permlane16_swap_b32_e32 v33, v94
	v_add_f32_dpp v69, v69, v69 row_ror:1 row_mask:0xf bank_mask:0xf bound_ctrl:1
	v_add_f32_e32 v95, v33, v94
	v_mov_b32_e32 v33, v69
	s_nop 1
	v_permlane16_swap_b32_e32 v69, v33
	v_add_f32_e32 v94, v69, v33
	v_mov_b32_e32 v97, v95
	v_mov_b32_e32 v96, v94
	s_nop 0
	v_permlane32_swap_b32_e32 v95, v97
	v_permlane32_swap_b32_e32 v94, v96
	v_pk_add_f32 v[94:95], v[94:95], v[96:97]
	s_nop 0
	v_pk_mul_f32 v[122:123], v[94:95], s[24:25] op_sel_hi:[1,0]
	s_nop 0
	v_fma_f32 v33, -v123, v123, v122
	v_max_f32_e32 v33, 0, v33
	v_add_f32_e32 v33, 0x3727c5ac, v33
	v_mul_f32_e32 v69, 0x4b800000, v33
	v_cmp_gt_f32_e32 vcc, s33, v33
	v_pk_add_f32 v[28:29], v[28:29], v[122:123] op_sel:[0,1] neg_lo:[0,1] neg_hi:[0,1]
	v_pk_add_f32 v[30:31], v[30:31], v[122:123] op_sel:[0,1] neg_lo:[0,1] neg_hi:[0,1]
	v_cndmask_b32_e32 v33, v33, v69, vcc
	v_rsq_f32_e32 v33, v33
	v_pk_add_f32 v[24:25], v[24:25], v[122:123] op_sel:[0,1] neg_lo:[0,1] neg_hi:[0,1]
	v_pk_add_f32 v[26:27], v[26:27], v[122:123] op_sel:[0,1] neg_lo:[0,1] neg_hi:[0,1]
	v_pk_add_f32 v[20:21], v[20:21], v[122:123] op_sel:[0,1] neg_lo:[0,1] neg_hi:[0,1]
	v_mul_f32_e32 v69, 0x45800000, v33
	v_cndmask_b32_e32 v124, v33, v69, vcc
	v_pk_mul_f32 v[28:29], v[28:29], v[124:125] op_sel_hi:[1,0]
	v_pk_mul_f32 v[30:31], v[30:31], v[124:125] op_sel_hi:[1,0]
	s_waitcnt vmcnt(2)
	v_pk_fma_f32 v[28:29], v[74:75], v[28:29], v[78:79]
	s_waitcnt vmcnt(0)
	v_pk_add_f32 v[74:75], v[86:87], 1.0 op_sel_hi:[1,0]
	v_ashrrev_i32_e32 v33, 31, v32
	v_pk_fma_f32 v[28:29], v[74:75], v[28:29], v[82:83]
	v_pk_fma_f32 v[30:31], v[76:77], v[30:31], v[80:81]
	v_pk_add_f32 v[74:75], v[88:89], 1.0 op_sel_hi:[1,0]
	v_lshlrev_b64 v[94:95], 11, v[32:33]
	v_pk_fma_f32 v[30:31], v[30:31], v[74:75], v[84:85]
	v_cvt_pk_bf16_f32 v74, v28, v29
	v_cvt_pk_bf16_f32 v75, v30, v31
	v_lshl_add_u64 v[126:127], v[58:59], 0, v[94:95]
	global_store_dwordx2 v[126:127], v[74:75], off
	v_lshl_add_u64 v[82:83], v[92:93], 0, v[62:63]
	global_load_dwordx4 v[74:77], v[42:43], off
	global_load_dwordx4 v[78:81], v[44:45], off
	s_nop 0
	global_load_dwordx4 v[82:85], v[82:83], off
	v_lshl_add_u64 v[86:87], v[90:91], 0, v[62:63]
	global_load_dwordx4 v[86:89], v[86:87], off
	v_pk_mul_f32 v[24:25], v[24:25], v[124:125] op_sel_hi:[1,0]
	v_pk_mul_f32 v[26:27], v[26:27], v[124:125] op_sel_hi:[1,0]
	v_lshl_add_u64 v[94:95], v[92:93], 0, v[64:65]
	v_pk_add_f32 v[22:23], v[22:23], v[122:123] op_sel:[0,1] neg_lo:[0,1] neg_hi:[0,1]
	v_pk_mul_f32 v[20:21], v[20:21], v[124:125] op_sel_hi:[1,0]
	v_pk_mul_f32 v[22:23], v[22:23], v[124:125] op_sel_hi:[1,0]
	v_lshl_add_u64 v[92:93], v[92:93], 0, v[66:67]
	v_pk_add_f32 v[16:17], v[16:17], v[122:123] op_sel:[0,1] neg_lo:[0,1] neg_hi:[0,1]
	v_pk_add_f32 v[18:19], v[18:19], v[122:123] op_sel:[0,1] neg_lo:[0,1] neg_hi:[0,1]
	v_pk_mul_f32 v[16:17], v[16:17], v[124:125] op_sel_hi:[1,0]
	v_pk_mul_f32 v[18:19], v[18:19], v[124:125] op_sel_hi:[1,0]
	s_waitcnt vmcnt(2)
	v_pk_fma_f32 v[24:25], v[24:25], v[74:75], v[78:79]
	s_waitcnt vmcnt(1)
	v_pk_add_f32 v[74:75], v[82:83], 1.0 op_sel_hi:[1,0]
	v_pk_fma_f32 v[76:77], v[26:27], v[76:77], v[80:81]
	v_pk_add_f32 v[78:79], v[84:85], 1.0 op_sel_hi:[1,0]
	s_waitcnt vmcnt(0)
	v_pk_fma_f32 v[26:27], v[24:25], v[74:75], v[86:87]
	v_pk_fma_f32 v[24:25], v[76:77], v[78:79], v[88:89]
	v_cvt_pk_bf16_f32 v74, v26, v27
	v_cvt_pk_bf16_f32 v75, v24, v25
	global_store_dwordx2 v[126:127], v[74:75], off offset:512
	global_load_dwordx4 v[74:77], v[46:47], off
	s_nop 0
	global_load_dwordx4 v[78:81], v[48:49], off
	global_load_dwordx4 v[82:85], v[94:95], off
	v_lshl_add_u64 v[86:87], v[90:91], 0, v[64:65]
	global_load_dwordx4 v[86:89], v[86:87], off
	s_waitcnt vmcnt(2)
	v_pk_fma_f32 v[20:21], v[20:21], v[74:75], v[78:79]
	s_waitcnt vmcnt(1)
	v_pk_add_f32 v[74:75], v[82:83], 1.0 op_sel_hi:[1,0]
	v_pk_fma_f32 v[76:77], v[22:23], v[76:77], v[80:81]
	v_pk_add_f32 v[78:79], v[84:85], 1.0 op_sel_hi:[1,0]
	s_waitcnt vmcnt(0)
	v_pk_fma_f32 v[22:23], v[20:21], v[74:75], v[86:87]
	v_pk_fma_f32 v[20:21], v[76:77], v[78:79], v[88:89]
	v_cvt_pk_bf16_f32 v74, v22, v23
	v_cvt_pk_bf16_f32 v75, v20, v21
	global_store_dwordx2 v[126:127], v[74:75], off offset:1024
	global_load_dwordx4 v[74:77], v[50:51], off
	s_nop 0
	global_load_dwordx4 v[78:81], v[52:53], off
	global_load_dwordx4 v[82:85], v[92:93], off
	v_lshl_add_u64 v[86:87], v[90:91], 0, v[66:67]
	global_load_dwordx4 v[86:89], v[86:87], off
	ds_read_b128 v[90:93], v36
	ds_read_b128 v[94:97], v36 offset:1024
	ds_read_b128 v[98:101], v36 offset:2048
	ds_read_b128 v[102:105], v36 offset:3072
	ds_read_b128 v[106:109], v36 offset:7168
	ds_read_b128 v[110:113], v36 offset:6144
	ds_read_b128 v[114:117], v36 offset:5120
	ds_read_b128 v[118:121], v36 offset:4096
	s_waitcnt lgkmcnt(7)
	v_mul_f32_e32 v69, v29, v91
	v_fmac_f32_e32 v69, v28, v90
	v_fmac_f32_e32 v69, v30, v92
	s_waitcnt lgkmcnt(1)
	v_mul_f32_e32 v92, v26, v114
	s_waitcnt lgkmcnt(0)
	v_mul_f32_e32 v91, v28, v118
	v_fmac_f32_e32 v91, v29, v119
	v_fmac_f32_e32 v91, v30, v120
	v_fmac_f32_e32 v91, v31, v121
	v_add_f32_e32 v90, 0, v91
	v_mul_f32_e32 v91, v27, v95
	v_fmac_f32_e32 v91, v26, v94
	v_fmac_f32_e32 v92, v27, v115
	v_fmac_f32_e32 v69, v31, v93
	v_fmac_f32_e32 v91, v24, v96
	v_fmac_f32_e32 v92, v24, v116
	v_add_f32_e32 v69, 0, v69
	v_fmac_f32_e32 v91, v25, v97
	v_fmac_f32_e32 v92, v25, v117
	v_add_f32_e32 v69, v69, v91
	v_add_f32_e32 v90, v92, v90
	v_mul_f32_e32 v91, v23, v99
	v_mul_f32_e32 v92, v22, v110
	v_fmac_f32_e32 v91, v22, v98
	v_fmac_f32_e32 v92, v23, v111
	v_fmac_f32_e32 v91, v20, v100
	v_fmac_f32_e32 v92, v20, v112
	v_fmac_f32_e32 v91, v21, v101
	v_fmac_f32_e32 v92, v21, v113
	v_add_f32_e32 v69, v69, v91
	v_add_f32_e32 v90, v92, v90
	s_waitcnt vmcnt(2)
	v_pk_fma_f32 v[16:17], v[16:17], v[74:75], v[78:79]
	s_waitcnt vmcnt(1)
	v_pk_add_f32 v[74:75], v[82:83], 1.0 op_sel_hi:[1,0]
	v_pk_fma_f32 v[76:77], v[18:19], v[76:77], v[80:81]
	v_pk_add_f32 v[78:79], v[84:85], 1.0 op_sel_hi:[1,0]
	s_waitcnt vmcnt(0)
	v_pk_fma_f32 v[18:19], v[16:17], v[74:75], v[86:87]
	v_pk_fma_f32 v[16:17], v[76:77], v[78:79], v[88:89]
	v_mul_f32_e32 v76, v19, v103
	v_mul_f32_e32 v77, v18, v106
	v_fmac_f32_e32 v76, v18, v102
	v_fmac_f32_e32 v77, v19, v107
	v_fmac_f32_e32 v76, v16, v104
	v_fmac_f32_e32 v77, v16, v108
	v_cvt_pk_bf16_f32 v74, v18, v19
	v_cvt_pk_bf16_f32 v75, v16, v17
	v_fmac_f32_e32 v76, v17, v105
	v_fmac_f32_e32 v77, v17, v109
	global_store_dwordx2 v[126:127], v[74:75], off offset:1536
	v_add_f32_e32 v74, v69, v76
	v_add_f32_e32 v69, v77, v90
	s_and_b64 vcc, exec, s[18:19]
	s_cbranch_vccz .Lr13_nopf
	v_ashrrev_i32_e32 v1, 31, v68
	v_mov_b32_e32 v0, v68
	v_lshlrev_b64 v[0:1], 12, v[0:1]
	v_lshl_add_u64 v[12:13], v[54:55], 0, v[0:1]
	global_load_dwordx4 v[0:3], v[12:13], off
	global_load_dwordx4 v[4:7], v[12:13], off offset:1024
	global_load_dwordx4 v[8:11], v[12:13], off offset:2048
	s_nop 0
	global_load_dwordx4 v[12:15], v[12:13], off offset:3072
.Lr13_nopf:
	ds_read_b128 v[168:171], v36 offset:8192
	ds_read_b128 v[172:175], v36 offset:9216
	ds_read_b128 v[176:179], v36 offset:10240
	ds_read_b128 v[180:183], v36 offset:11264
	ds_read_b128 v[184:187], v36 offset:12288
	ds_read_b128 v[188:191], v36 offset:13312
	ds_read_b128 v[192:195], v36 offset:14336
	ds_read_b128 v[196:199], v36 offset:15360
	ds_read_b128 v[200:203], v36 offset:16384
	ds_read_b128 v[204:207], v36 offset:17408
	ds_read_b128 v[208:211], v36 offset:18432
	ds_read_b128 v[212:215], v36 offset:19456
	s_waitcnt lgkmcnt(8)
	v_pk_mul_f32 v[216:217], v[28:29], v[168:169]
	v_pk_fma_f32 v[216:217], v[30:31], v[170:171], v[216:217]
	v_pk_fma_f32 v[216:217], v[26:27], v[172:173], v[216:217]
	v_pk_fma_f32 v[216:217], v[24:25], v[174:175], v[216:217]
	v_pk_fma_f32 v[216:217], v[22:23], v[176:177], v[216:217]
	v_pk_fma_f32 v[216:217], v[20:21], v[178:179], v[216:217]
	v_pk_fma_f32 v[216:217], v[18:19], v[180:181], v[216:217]
	v_pk_fma_f32 v[216:217], v[16:17], v[182:183], v[216:217]
	ds_read_b128 v[168:171], v36 offset:20480
	ds_read_b128 v[172:175], v36 offset:21504
	ds_read_b128 v[176:179], v36 offset:22528
	ds_read_b128 v[180:183], v36 offset:23552
	v_add_f32_e32 v75, v216, v217
	s_waitcnt lgkmcnt(8)
	v_pk_mul_f32 v[216:217], v[28:29], v[184:185]
	v_pk_fma_f32 v[216:217], v[30:31], v[186:187], v[216:217]
	v_pk_fma_f32 v[216:217], v[26:27], v[188:189], v[216:217]
	v_pk_fma_f32 v[216:217], v[24:25], v[190:191], v[216:217]
	v_pk_fma_f32 v[216:217], v[22:23], v[192:193], v[216:217]
	v_pk_fma_f32 v[216:217], v[20:21], v[194:195], v[216:217]
	v_pk_fma_f32 v[216:217], v[18:19], v[196:197], v[216:217]
	v_pk_fma_f32 v[216:217], v[16:17], v[198:199], v[216:217]
	ds_read_b128 v[184:187], v36 offset:24576
	ds_read_b128 v[188:191], v36 offset:25600
	ds_read_b128 v[192:195], v36 offset:26624
	ds_read_b128 v[196:199], v36 offset:27648
	v_add_f32_e32 v76, v216, v217
	s_waitcnt lgkmcnt(8)
	v_pk_mul_f32 v[216:217], v[28:29], v[200:201]
	v_pk_fma_f32 v[216:217], v[30:31], v[202:203], v[216:217]
	v_pk_fma_f32 v[216:217], v[26:27], v[204:205], v[216:217]
	v_pk_fma_f32 v[216:217], v[24:25], v[206:207], v[216:217]
	v_pk_fma_f32 v[216:217], v[22:23], v[208:209], v[216:217]
	v_pk_fma_f32 v[216:217], v[20:21], v[210:211], v[216:217]
	v_pk_fma_f32 v[216:217], v[18:19], v[212:213], v[216:217]
	v_pk_fma_f32 v[216:217], v[16:17], v[214:215], v[216:217]
	ds_read_b128 v[200:203], v36 offset:28672
	ds_read_b128 v[204:207], v36 offset:29696
	ds_read_b128 v[208:211], v36 offset:30720
	ds_read_b128 v[212:215], v36 offset:31744
	v_add_f32_e32 v77, v216, v217
	s_waitcnt lgkmcnt(8)
	v_pk_mul_f32 v[216:217], v[28:29], v[168:169]
	v_pk_fma_f32 v[216:217], v[30:31], v[170:171], v[216:217]
	v_pk_fma_f32 v[216:217], v[26:27], v[172:173], v[216:217]
	v_pk_fma_f32 v[216:217], v[24:25], v[174:175], v[216:217]
	v_pk_fma_f32 v[216:217], v[22:23], v[176:177], v[216:217]
	v_pk_fma_f32 v[216:217], v[20:21], v[178:179], v[216:217]
	v_pk_fma_f32 v[216:217], v[18:19], v[180:181], v[216:217]
	v_pk_fma_f32 v[216:217], v[16:17], v[182:183], v[216:217]
	ds_read_b128 v[168:171], v36 offset:32768
	ds_read_b128 v[172:175], v36 offset:33792
	ds_read_b128 v[176:179], v36 offset:34816
	ds_read_b128 v[180:183], v36 offset:35840
	v_add_f32_e32 v94, v216, v217
	s_waitcnt lgkmcnt(8)
	v_pk_mul_f32 v[216:217], v[28:29], v[184:185]
	v_pk_fma_f32 v[216:217], v[30:31], v[186:187], v[216:217]
	v_pk_fma_f32 v[216:217], v[26:27], v[188:189], v[216:217]
	v_pk_fma_f32 v[216:217], v[24:25], v[190:191], v[216:217]
	v_pk_fma_f32 v[216:217], v[22:23], v[192:193], v[216:217]
	v_pk_fma_f32 v[216:217], v[20:21], v[194:195], v[216:217]
	v_pk_fma_f32 v[216:217], v[18:19], v[196:197], v[216:217]
	v_pk_fma_f32 v[216:217], v[16:17], v[198:199], v[216:217]
	ds_read_b128 v[184:187], v36 offset:36864
	ds_read_b128 v[188:191], v36 offset:37888
	ds_read_b128 v[192:195], v36 offset:38912
	ds_read_b128 v[196:199], v36 offset:39936
	v_add_f32_e32 v95, v216, v217
	s_waitcnt lgkmcnt(8)
	v_pk_mul_f32 v[216:217], v[28:29], v[200:201]
	v_pk_fma_f32 v[216:217], v[30:31], v[202:203], v[216:217]
	v_pk_fma_f32 v[216:217], v[26:27], v[204:205], v[216:217]
	v_pk_fma_f32 v[216:217], v[24:25], v[206:207], v[216:217]
	v_pk_fma_f32 v[216:217], v[22:23], v[208:209], v[216:217]
	v_pk_fma_f32 v[216:217], v[20:21], v[210:211], v[216:217]
	v_pk_fma_f32 v[216:217], v[18:19], v[212:213], v[216:217]
	v_pk_fma_f32 v[216:217], v[16:17], v[214:215], v[216:217]
	ds_read_b128 v[200:203], v36 offset:40960
	ds_read_b128 v[204:207], v36 offset:41984
	ds_read_b128 v[208:211], v36 offset:43008
	ds_read_b128 v[212:215], v36 offset:44032
	v_add_f32_e32 v96, v216, v217
	s_waitcnt lgkmcnt(8)
	v_pk_mul_f32 v[216:217], v[28:29], v[168:169]
	v_pk_fma_f32 v[216:217], v[30:31], v[170:171], v[216:217]
	v_pk_fma_f32 v[216:217], v[26:27], v[172:173], v[216:217]
	v_pk_fma_f32 v[216:217], v[24:25], v[174:175], v[216:217]
	v_pk_fma_f32 v[216:217], v[22:23], v[176:177], v[216:217]
	v_pk_fma_f32 v[216:217], v[20:21], v[178:179], v[216:217]
	v_pk_fma_f32 v[216:217], v[18:19], v[180:181], v[216:217]
	v_pk_fma_f32 v[216:217], v[16:17], v[182:183], v[216:217]
	ds_read_b128 v[168:171], v36 offset:45056
	ds_read_b128 v[172:175], v36 offset:46080
	ds_read_b128 v[176:179], v36 offset:47104
	ds_read_b128 v[180:183], v36 offset:48128
	v_add_f32_e32 v97, v216, v217
	s_waitcnt lgkmcnt(8)
	v_pk_mul_f32 v[216:217], v[28:29], v[184:185]
	v_pk_fma_f32 v[216:217], v[30:31], v[186:187], v[216:217]
	v_pk_fma_f32 v[216:217], v[26:27], v[188:189], v[216:217]
	v_pk_fma_f32 v[216:217], v[24:25], v[190:191], v[216:217]
	v_pk_fma_f32 v[216:217], v[22:23], v[192:193], v[216:217]
	v_pk_fma_f32 v[216:217], v[20:21], v[194:195], v[216:217]
	v_pk_fma_f32 v[216:217], v[18:19], v[196:197], v[216:217]
	v_pk_fma_f32 v[216:217], v[16:17], v[198:199], v[216:217]
	ds_read_b128 v[184:187], v36 offset:49152
	ds_read_b128 v[188:191], v36 offset:50176
	ds_read_b128 v[192:195], v36 offset:51200
	ds_read_b128 v[196:199], v36 offset:52224
	v_add_f32_e32 v98, v216, v217
	s_waitcnt lgkmcnt(8)
	v_pk_mul_f32 v[216:217], v[28:29], v[200:201]
	v_pk_fma_f32 v[216:217], v[30:31], v[202:203], v[216:217]
	v_pk_fma_f32 v[216:217], v[26:27], v[204:205], v[216:217]
	v_pk_fma_f32 v[216:217], v[24:25], v[206:207], v[216:217]
	v_pk_fma_f32 v[216:217], v[22:23], v[208:209], v[216:217]
	v_pk_fma_f32 v[216:217], v[20:21], v[210:211], v[216:217]
	v_pk_fma_f32 v[216:217], v[18:19], v[212:213], v[216:217]
	v_pk_fma_f32 v[216:217], v[16:17], v[214:215], v[216:217]
	ds_read_b128 v[200:203], v36 offset:53248
	ds_read_b128 v[204:207], v36 offset:54272
	ds_read_b128 v[208:211], v36 offset:55296
	ds_read_b128 v[212:215], v36 offset:56320
	v_add_f32_e32 v99, v216, v217
	s_waitcnt lgkmcnt(8)
	v_pk_mul_f32 v[216:217], v[28:29], v[168:169]
	v_pk_fma_f32 v[216:217], v[30:31], v[170:171], v[216:217]
	v_pk_fma_f32 v[216:217], v[26:27], v[172:173], v[216:217]
	v_pk_fma_f32 v[216:217], v[24:25], v[174:175], v[216:217]
	v_pk_fma_f32 v[216:217], v[22:23], v[176:177], v[216:217]
	v_pk_fma_f32 v[216:217], v[20:21], v[178:179], v[216:217]
	v_pk_fma_f32 v[216:217], v[18:19], v[180:181], v[216:217]
	v_pk_fma_f32 v[216:217], v[16:17], v[182:183], v[216:217]
	ds_read_b128 v[168:171], v36 offset:57344
	ds_read_b128 v[172:175], v36 offset:58368
	ds_read_b128 v[176:179], v36 offset:59392
	ds_read_b128 v[180:183], v36 offset:60416
	v_add_f32_e32 v100, v216, v217
	s_waitcnt lgkmcnt(8)
	v_pk_mul_f32 v[216:217], v[28:29], v[184:185]
	v_pk_fma_f32 v[216:217], v[30:31], v[186:187], v[216:217]
	v_pk_fma_f32 v[216:217], v[26:27], v[188:189], v[216:217]
	v_pk_fma_f32 v[216:217], v[24:25], v[190:191], v[216:217]
	v_pk_fma_f32 v[216:217], v[22:23], v[192:193], v[216:217]
	v_pk_fma_f32 v[216:217], v[20:21], v[194:195], v[216:217]
	v_pk_fma_f32 v[216:217], v[18:19], v[196:197], v[216:217]
	v_pk_fma_f32 v[216:217], v[16:17], v[198:199], v[216:217]
	ds_read_b128 v[184:187], v36 offset:61440
	ds_read_b128 v[188:191], v36 offset:62464
	ds_read_b128 v[192:195], v36 offset:63488
	ds_read_b128 v[196:199], v36 offset:64512
	v_add_f32_e32 v101, v216, v217
	s_waitcnt lgkmcnt(8)
	v_pk_mul_f32 v[216:217], v[28:29], v[200:201]
	v_pk_fma_f32 v[216:217], v[30:31], v[202:203], v[216:217]
	v_pk_fma_f32 v[216:217], v[26:27], v[204:205], v[216:217]
	v_pk_fma_f32 v[216:217], v[24:25], v[206:207], v[216:217]
	v_pk_fma_f32 v[216:217], v[22:23], v[208:209], v[216:217]
	v_pk_fma_f32 v[216:217], v[20:21], v[210:211], v[216:217]
	v_pk_fma_f32 v[216:217], v[18:19], v[212:213], v[216:217]
	v_pk_fma_f32 v[216:217], v[16:17], v[214:215], v[216:217]
	v_add_f32_e32 v102, v216, v217
	s_waitcnt lgkmcnt(4)
	v_pk_mul_f32 v[216:217], v[28:29], v[168:169]
	v_pk_fma_f32 v[216:217], v[30:31], v[170:171], v[216:217]
	v_pk_fma_f32 v[216:217], v[26:27], v[172:173], v[216:217]
	v_pk_fma_f32 v[216:217], v[24:25], v[174:175], v[216:217]
	v_pk_fma_f32 v[216:217], v[22:23], v[176:177], v[216:217]
	v_pk_fma_f32 v[216:217], v[20:21], v[178:179], v[216:217]
	v_pk_fma_f32 v[216:217], v[18:19], v[180:181], v[216:217]
	v_pk_fma_f32 v[216:217], v[16:17], v[182:183], v[216:217]
	v_add_f32_e32 v103, v216, v217
	s_waitcnt lgkmcnt(0)
	v_pk_mul_f32 v[216:217], v[28:29], v[184:185]
	v_pk_fma_f32 v[216:217], v[30:31], v[186:187], v[216:217]
	v_pk_fma_f32 v[216:217], v[26:27], v[188:189], v[216:217]
	v_pk_fma_f32 v[216:217], v[24:25], v[190:191], v[216:217]
	v_pk_fma_f32 v[216:217], v[22:23], v[192:193], v[216:217]
	v_pk_fma_f32 v[216:217], v[20:21], v[194:195], v[216:217]
	v_pk_fma_f32 v[216:217], v[18:19], v[196:197], v[216:217]
	v_pk_fma_f32 v[216:217], v[16:17], v[198:199], v[216:217]
	v_add_f32_e32 v16, v216, v217
	v_cndmask_b32_e64 v18, v74, v97, s[0:1]
	v_mov_b32_e32 v19, v18
	s_nop 1
	v_permlane32_swap_b32_e32 v18, v19
	v_cndmask_b32_e64 v18, v18, v19, s[0:1]
	v_cndmask_b32_e64 v19, v69, v98, s[0:1]
	v_mov_b32_e32 v20, v19
	s_nop 1
	v_permlane32_swap_b32_e32 v19, v20
	v_cndmask_b32_e64 v19, v19, v20, s[0:1]
	v_cndmask_b32_e64 v20, v75, v99, s[0:1]
	v_mov_b32_e32 v21, v20
	s_nop 1
	v_permlane32_swap_b32_e32 v20, v21
	v_cndmask_b32_e64 v20, v20, v21, s[0:1]
	v_cndmask_b32_e64 v21, v76, v100, s[0:1]
	v_mov_b32_e32 v22, v21
	s_nop 1
	v_permlane32_swap_b32_e32 v21, v22
	v_cndmask_b32_e64 v21, v21, v22, s[0:1]
	v_cndmask_b32_e64 v22, v77, v101, s[0:1]
	v_mov_b32_e32 v23, v22
	s_nop 1
	v_permlane32_swap_b32_e32 v22, v23
	v_cndmask_b32_e64 v17, v97, v74, s[0:1]
	v_cndmask_b32_e64 v22, v22, v23, s[0:1]
	v_cndmask_b32_e64 v23, v94, v102, s[0:1]
	v_add_f32_e32 v17, v17, v18
	v_cndmask_b32_e64 v18, v98, v69, s[0:1]
	v_mov_b32_e32 v24, v23
	v_add_f32_e32 v18, v18, v19
	v_cndmask_b32_e64 v19, v99, v75, s[0:1]
	v_permlane32_swap_b32_e32 v23, v24
	v_add_f32_e32 v19, v19, v20
	v_cndmask_b32_e64 v20, v100, v76, s[0:1]
	v_cndmask_b32_e64 v23, v23, v24, s[0:1]
	v_cndmask_b32_e64 v24, v95, v103, s[0:1]
	v_add_f32_e32 v20, v20, v21
	v_cndmask_b32_e64 v21, v101, v77, s[0:1]
	v_mov_b32_e32 v25, v24
	v_add_f32_e32 v21, v21, v22
	v_cndmask_b32_e64 v22, v102, v94, s[0:1]
	v_permlane32_swap_b32_e32 v24, v25
	v_add_f32_e32 v22, v22, v23
	v_cndmask_b32_e64 v23, v103, v95, s[0:1]
	v_cndmask_b32_e64 v24, v24, v25, s[0:1]
	v_add_f32_e32 v23, v23, v24
	v_cndmask_b32_e64 v24, v16, v96, s[0:1]
	v_cndmask_b32_e64 v16, v96, v16, s[0:1]
	v_mov_b32_e32 v25, v16
	s_nop 1
	v_permlane32_swap_b32_e32 v16, v25
	v_cndmask_b32_e64 v16, v16, v25, s[0:1]
	v_add_f32_e32 v16, v24, v16
	v_cndmask_b32_e64 v24, v21, v17, s[16:17]
	v_cndmask_b32_e64 v17, v17, v21, s[16:17]
	v_mov_b32_e32 v21, v17
	s_nop 1
	v_permlane16_swap_b32_e32 v17, v21
	v_cndmask_b32_e64 v17, v17, v21, s[16:17]
	v_cndmask_b32_e64 v21, v22, v18, s[16:17]
	v_cndmask_b32_e64 v18, v18, v22, s[16:17]
	v_mov_b32_e32 v22, v18
	s_nop 1
	v_permlane16_swap_b32_e32 v18, v22
	v_cndmask_b32_e64 v18, v18, v22, s[16:17]
	v_add_f32_e32 v18, v21, v18
	v_cndmask_b32_e64 v21, v23, v19, s[16:17]
	v_cndmask_b32_e64 v19, v19, v23, s[16:17]
	v_mov_b32_e32 v22, v19
	s_nop 1
	v_permlane16_swap_b32_e32 v19, v22
	v_cndmask_b32_e64 v19, v19, v22, s[16:17]
	v_add_f32_e32 v19, v21, v19
	v_cndmask_b32_e64 v21, v16, v20, s[16:17]
	v_cndmask_b32_e64 v16, v20, v16, s[16:17]
	v_mov_b32_e32 v20, v16
	s_nop 1
	v_permlane16_swap_b32_e32 v16, v20
	v_cndmask_b32_e64 v16, v16, v20, s[16:17]
	v_add_f32_e32 v17, v24, v17
	v_add_f32_e32 v16, v21, v16
	v_cndmask_b32_e64 v20, v17, v19, s[4:5]
	v_cndmask_b32_e64 v21, v18, v16, s[4:5]
	ds_bpermute_b32 v20, v70, v20
	ds_bpermute_b32 v21, v70, v21
	v_cndmask_b32_e64 v17, v19, v17, s[4:5]
	v_cndmask_b32_e64 v16, v16, v18, s[4:5]
	s_waitcnt lgkmcnt(1)
	v_add_f32_e32 v17, v17, v20
	s_waitcnt lgkmcnt(0)
	v_add_f32_e32 v16, v16, v21
	v_cndmask_b32_e64 v18, v17, v16, s[6:7]
	ds_bpermute_b32 v18, v71, v18
	v_cndmask_b32_e64 v16, v16, v17, s[6:7]
	s_waitcnt lgkmcnt(0)
	v_add_f32_e32 v16, v16, v18
	ds_bpermute_b32 v17, v72, v16
	s_waitcnt lgkmcnt(0)
	v_add_f32_e32 v16, v16, v17
	ds_bpermute_b32 v17, v73, v16
	s_waitcnt lgkmcnt(0)
	v_add_f32_e32 v16, v16, v17
	ds_bpermute_b32 v17, v70, v16
	s_waitcnt lgkmcnt(0)
	v_max_f32_e32 v17, v17, v17
	v_max_f32_e32 v17, v16, v17
	ds_bpermute_b32 v18, v71, v17
	s_waitcnt lgkmcnt(0)
	v_max_f32_e32 v18, v18, v18
	v_max_f32_e32 v17, v17, v18
	v_mov_b32_e32 v18, v17
	s_nop 1
	v_permlane16_swap_b32_e32 v17, v18
	v_max_f32_e32 v18, v18, v18
	v_max_f32_e32 v17, v17, v17
	v_max_f32_e32 v17, v17, v18
	v_mov_b32_e32 v18, v17
	s_nop 1
	v_permlane32_swap_b32_e32 v17, v18
	v_max_f32_e32 v18, v18, v18
	v_max_f32_e32 v17, v17, v17
	v_max_f32_e32 v17, v17, v18
	v_sub_f32_e32 v16, v16, v17
	v_mul_f32_e32 v17, 0x3fb8aa3b, v16
	v_fma_f32 v18, v16, s34, -v17
	v_rndne_f32_e32 v19, v17
	v_fmac_f32_e32 v18, 0x32a5705f, v16
	v_sub_f32_e32 v17, v17, v19
	v_add_f32_e32 v17, v17, v18
	v_exp_f32_e32 v17, v17
	v_cvt_i32_f32_e32 v18, v19
	v_cmp_ngt_f32_e32 vcc, s35, v16
	v_ldexp_f32 v17, v17, v18
	s_nop 0
	v_cndmask_b32_e32 v17, 0, v17, vcc
	v_cmp_nlt_f32_e32 vcc, s36, v16
	s_nop 1
	v_cndmask_b32_e32 v16, v37, v17, vcc
	ds_bpermute_b32 v17, v70, v16
	s_waitcnt lgkmcnt(0)
	v_add_f32_e32 v17, v16, v17
	ds_bpermute_b32 v18, v71, v17
	s_waitcnt lgkmcnt(0)
	v_add_f32_e32 v17, v17, v18
	v_mov_b32_e32 v18, v17
	s_nop 1
	v_permlane16_swap_b32_e32 v17, v18
	v_add_f32_e32 v17, v17, v18
	v_mov_b32_e32 v18, v17
	s_nop 1
	v_permlane32_swap_b32_e32 v17, v18
	s_and_saveexec_b64 s[2:3], s[8:9]
	s_cbranch_execz .LBB0_1873
	v_add_f32_e32 v17, v17, v18
	v_div_scale_f32 v18, s[18:19], v17, v17, v16
	v_rcp_f32_e32 v19, v18
	v_div_scale_f32 v20, vcc, v16, v17, v16
	v_fma_f32 v21, -v18, v19, 1.0
	v_fmac_f32_e32 v19, v21, v19
	v_mul_f32_e32 v21, v20, v19
	v_fma_f32 v22, -v18, v21, v20
	v_fmac_f32_e32 v21, v22, v19
	v_fma_f32 v18, -v18, v21, v20
	v_div_fmas_f32 v18, v18, v19, v21
	v_div_fixup_f32 v18, v18, v17, v16
	v_lshlrev_b64 v[16:17], 6, v[32:33]
	v_lshl_add_u64 v[16:17], v[56:57], 0, v[16:17]
	global_store_dword v[16:17], v18, off
